# P13: chunk-scan blocks permuted so the 32 heads of one batch run on one XCD (shared B/C in that L2)
# speedup vs baseline: 1.0044x; 1.0044x over previous
.LBB0_2445:
	s_or_b64 exec, exec, s[0:1]
	v_readlane_b32 s98, v245, 0
	v_readlane_b32 s99, v245, 9
	s_nop 3
	v_writelane_b32 v244, s98, 62
	s_cmpk_lg_u32 s99, 0x200
	s_cbranch_scc1 .Lp13x_go
	s_cmpk_lt_u32 s98, 0x100
	s_cbranch_scc0 .Lp13x_go
	s_and_b32 s99, s98, 7
	s_lshl_b32 s99, s99, 5
	s_lshr_b32 s98, s98, 3
	s_or_b32 s99, s99, s98
	s_nop 0
	v_writelane_b32 v245, s99, 0
	s_nop 1
